# DSA sparse attention: first V-fragment batch read before the softmax VALU, second batch under the first batch's MFMAs
# speedup vs baseline: 1.0023x; 1.0005x over previous
; DI f32x16 mfma32(bf16x8 a, bf16x8 b, f32x16 c) { return __builtin_amdgcn_mfma_f32_32x32x16_bf16(a, b, c, 0, 0, 0); }
; DI int crow(int i, int hh) { return (i & 3) + 8 * (i >> 2) + 4 * hh; }
; DI void dsa_item(const Params& p, int l, int tile32, int b, char* smem) {
;     ...
;       for (int j = 0; j < 16; ++j) {
;         if (tt * 32 + crow(j, hh) >= nsel) sa[j] = -INFINITY;
;         tmax = fmaxf(tmax, sa[j]);
;       }
;       tmax = xhalf_max(tmax);
;       const float cand = tmax * sc;
;       if (__any(cand > mrun + 8.f)) {
;         const float mnew = fmaxf(mrun, cand);
;         const float alpha = __builtin_amdgcn_exp2f(mrun - mnew);
;         mrun = mnew;
;         lrun *= alpha;
; #pragma unroll
;         for (int i = 0; i < 4; ++i)
; #pragma unroll
;           for (int j = 0; j < 16; ++j) O[i][j] *= alpha;
;       }
;       float psum = 0.f;
; #pragma unroll
;       for (int j = 0; j < 16; ++j) { const float pv = __builtin_amdgcn_exp2f(sa[j] * sc - mrun); sa[j] = pv; psum += pv; }
;       lrun += psum;
; #pragma unroll
;       for (int s2 = 0; s2 < 2; ++s2) {
;         const bf16x8 pp = pack8(sa, s2);
;         bf16x8 vf[4];
;         trfrag4<272>(tile, 16 * s2, ln, vf);
; #pragma unroll
;         for (int mt = 0; mt < 4; ++mt) O[mt] = mfma32(vf[mt], pp, O[mt]);
;       }
.LBB0_566:
	ds_read_b64_tr_b16 v[226:227], v209
	ds_read_b64_tr_b16 v[228:229], v209 offset:2176
	ds_read_b64_tr_b16 v[230:231], v209 offset:64
	ds_read_b64_tr_b16 v[232:233], v209 offset:2240
	ds_read_b64_tr_b16 v[234:235], v209 offset:128
	ds_read_b64_tr_b16 v[236:237], v209 offset:2304
	ds_read_b64_tr_b16 v[238:239], v209 offset:192
	ds_read_b64_tr_b16 v[240:241], v209 offset:2368
	s_or_b64 vcc, s[30:31], s[28:29]
	v_cndmask_b32_e32 v14, v14, v93, vcc
	s_or_b64 vcc, vcc, s[26:27]
	v_cndmask_b32_e32 v13, v13, v92, vcc
	s_or_b64 vcc, vcc, s[24:25]
	v_cndmask_b32_e32 v12, v12, v91, vcc
	s_or_b64 vcc, vcc, s[22:23]
	v_cndmask_b32_e32 v11, v11, v90, vcc
	s_or_b64 vcc, vcc, s[20:21]
	v_cndmask_b32_e32 v10, v10, v89, vcc
	s_or_b64 vcc, vcc, s[18:19]
	v_cndmask_b32_e32 v9, v9, v88, vcc
	s_or_b64 vcc, vcc, s[16:17]
	v_cndmask_b32_e32 v8, v8, v87, vcc
	s_or_b64 vcc, vcc, s[14:15]
	v_cndmask_b32_e32 v7, v7, v86, vcc
	s_or_b64 vcc, vcc, s[12:13]
	v_cndmask_b32_e32 v6, v6, v85, vcc
	s_or_b64 vcc, vcc, s[10:11]
	v_cndmask_b32_e32 v5, v5, v84, vcc
	s_or_b64 vcc, vcc, s[8:9]
	v_cndmask_b32_e32 v4, v4, v83, vcc
	s_or_b64 vcc, vcc, s[6:7]
	v_cndmask_b32_e32 v3, v3, v82, vcc
	s_or_b64 vcc, vcc, s[4:5]
	v_cndmask_b32_e32 v2, v2, v81, vcc
	s_or_b64 vcc, vcc, s[2:3]
	v_cndmask_b32_e32 v0, v0, v80, vcc
	v_fma_f32 v0, v0, s58, -v211
	v_exp_f32_e32 v0, v0
	v_fma_f32 v2, v2, s58, -v211
	v_exp_f32_e32 v2, v2
	v_fma_f32 v3, v3, s58, -v211
	v_exp_f32_e32 v3, v3
	v_fma_f32 v4, v4, s58, -v211
	v_exp_f32_e32 v82, v4
	v_add_f32_e32 v81, 0, v0
	v_add_f32_e32 v81, v2, v81
	v_add_f32_e32 v81, v3, v81
	v_fma_f32 v5, v5, s58, -v211
	v_add_f32_e32 v4, v82, v81
	v_exp_f32_e32 v81, v5
	v_fma_f32 v5, v6, s58, -v211
	v_exp_f32_e32 v6, v5
	v_fma_f32 v5, v7, s58, -v211
	v_exp_f32_e32 v5, v5
	v_fma_f32 v7, v8, s58, -v211
	v_exp_f32_e32 v7, v7
	v_fma_f32 v8, v9, s58, -v211
	v_add_f32_e32 v4, v81, v4
	v_exp_f32_e32 v88, v8
	v_fma_f32 v8, v10, s58, -v211
	v_add_f32_e32 v4, v6, v4
	v_exp_f32_e32 v89, v8
	v_fma_f32 v8, v11, s58, -v211
	v_add_f32_e32 v4, v5, v4
	v_exp_f32_e32 v90, v8
	v_fma_f32 v8, v12, s58, -v211
	v_add_f32_e32 v4, v7, v4
	v_exp_f32_e32 v91, v8
	v_fma_f32 v8, v13, s58, -v211
	v_cndmask_b32_e64 v80, v212, v94, s[30:31]
	v_add_f32_e32 v4, v88, v4
	v_exp_f32_e32 v92, v8
	v_fma_f32 v8, v14, s58, -v211
	v_add_f32_e32 v4, v89, v4
	v_exp_f32_e32 v14, v8
	v_fma_f32 v8, v80, s58, -v211
	v_add_f32_e32 v4, v90, v4
	v_exp_f32_e32 v93, v8
	v_fma_f32 v8, v15, s58, -v211
	v_add_f32_e32 v4, v91, v4
	v_exp_f32_e32 v15, v8
	v_add_f32_e32 v4, v92, v4
	v_add_f32_e32 v4, v14, v4
	v_add_f32_e32 v4, v93, v4
	v_add_f32_e32 v94, v15, v4
	v_cvt_pk_bf16_f32 v5, v5, v7
	v_cvt_pk_bf16_f32 v4, v81, v6
	v_cvt_pk_bf16_f32 v3, v3, v82
	ds_read_b64_tr_b16 v[6:7], v209 offset:4352
	ds_read_b64_tr_b16 v[8:9], v209 offset:6528
	ds_read_b64_tr_b16 v[10:11], v209 offset:4416
	ds_read_b64_tr_b16 v[12:13], v209 offset:6592
	ds_read_b64_tr_b16 v[80:81], v209 offset:4480
	ds_read_b64_tr_b16 v[82:83], v209 offset:6656
	ds_read_b64_tr_b16 v[84:85], v209 offset:4544
	ds_read_b64_tr_b16 v[86:87], v209 offset:6720
	v_cvt_pk_bf16_f32 v2, v0, v2
	v_cmp_eq_u32_e32 vcc, s39, v169
	v_add_f32_e32 v165, v165, v94
	s_waitcnt lgkmcnt(8)
	v_mfma_f32_32x32x16_bf16 v[64:79], v[226:229], v[2:5], v[64:79]
	v_add_u32_e32 v210, 32, v210
	v_add_u32_e32 v179, 64, v179
	s_or_b64 s[36:37], vcc, s[36:37]
	s_waitcnt lgkmcnt(8)
	v_mfma_f32_32x32x16_bf16 v[48:63], v[230:233], v[2:5], v[48:63]
	s_waitcnt lgkmcnt(8)
	v_mfma_f32_32x32x16_bf16 v[32:47], v[234:237], v[2:5], v[32:47]
	s_waitcnt lgkmcnt(8)
	v_mfma_f32_32x32x16_bf16 v[16:31], v[238:241], v[2:5], v[16:31]
	v_cvt_pk_bf16_f32 v5, v93, v15
	v_cvt_pk_bf16_f32 v4, v92, v14
	v_cvt_pk_bf16_f32 v3, v90, v91
	v_cvt_pk_bf16_f32 v2, v88, v89
	s_waitcnt lgkmcnt(6)
	s_nop 0
	v_mfma_f32_32x32x16_bf16 v[64:79], v[6:9], v[2:5], v[64:79]
	s_waitcnt lgkmcnt(4)
	v_mfma_f32_32x32x16_bf16 v[48:63], v[10:13], v[2:5], v[48:63]
	s_waitcnt lgkmcnt(2)
	v_mfma_f32_32x32x16_bf16 v[32:47], v[80:83], v[2:5], v[32:47]
	s_waitcnt lgkmcnt(0)
	v_mfma_f32_32x32x16_bf16 v[16:31], v[84:87], v[2:5], v[16:31]
	s_andn2_b64 exec, exec, s[36:37]
	s_cbranch_execz .LBB0_571
